# rwkv_out staging: all RHO/Y0/V loads issued together (was 6 serialized round trips) + gate-lora loads for the 4 row groups issued together
# speedup vs baseline: 1.0196x; 1.0040x over previous
; __device__ __forceinline__ void rwkv_out_phase(const bf16* Z, const RwkvW w, const bf16* Wl, const float* Ub, const bf16* RHO, const bf16* Y0, const float* BON, bf16* MIX, unsigned char* lds) {
;     ...
;         for (int ci = tid; ci < 1024; ci += NTHR) { const int j = ci >> 3, c8 = (ci & 7) * 8;
;             *(u32x4*)(Rs + j * 72 + c8) = *(const u32x4*)(RHO + (rowbase + j) * 512 + col0 + c8);
;             *(u32x4*)(Ys + j * 72 + c8) = *(const u32x4*)(Y0 + (rowbase + j) * 512 + col0 + c8);
;             *(u32x4*)(Vs + (j + 1) * 72 + c8) = *(const u32x4*)(Z + (rowbase + j) * EVEN_IN + 3072 + col0 + c8); }
.LBB0_644:
	v_ashrrev_i32_e32 v8, 3, v3
	v_ashrrev_i32_e32 v9, 31, v8
	v_lshl_add_u64 v[10:11], s[16:17], 0, v[8:9]
	v_lshlrev_b64 v[12:13], 10, v[10:11]
	v_lshlrev_b32_e32 v0, 1, v2
	v_lshl_add_u64 v[4:5], s[20:21], 0, v[12:13]
	v_and_b32_e32 v0, 0x70, v0
	v_lshl_add_u64 v[4:5], v[4:5], 0, v[0:1]
	s_mov_b64 s[24:25], 0x10000
	global_load_dwordx4 v[114:117], v[4:5], off
	v_lshl_add_u64 v[6:7], v[4:5], 0, s[24:25]
	global_load_dwordx4 v[118:121], v[6:7], off
	v_lshl_add_u64 v[4:5], s[22:23], 0, v[12:13]
	v_lshl_add_u64 v[4:5], v[4:5], 0, v[0:1]
	global_load_dwordx4 v[122:125], v[4:5], off
	v_lshl_add_u64 v[6:7], v[4:5], 0, s[24:25]
	global_load_dwordx4 v[126:129], v[6:7], off
	v_mov_b64_e32 v[4:5], s[94:95]
	v_mad_u64_u32 v[4:5], s[42:43], v10, s65, v[4:5]
	v_mov_b32_e32 v6, v5
	v_mad_u64_u32 v[6:7], s[42:43], v11, s65, v[6:7]
	v_mov_b32_e32 v5, v6
	v_lshl_add_u64 v[4:5], v[4:5], 0, s[60:61]
	v_lshl_add_u64 v[4:5], v[4:5], 0, v[0:1]
	v_add_co_u32_e32 v4, vcc, 0x1000, v4
	s_mov_b64 s[24:25], 0x78000
	s_nop 0
	v_addc_co_u32_e32 v5, vcc, 0, v5, vcc
	global_load_dwordx4 v[130:133], v[4:5], off offset:2048
	v_lshl_add_u64 v[6:7], v[4:5], 0, s[24:25]
	global_load_dwordx4 v[134:137], v[6:7], off offset:2048
	v_mul_lo_u32 v8, v8, s64
	v_add3_u32 v9, 0, v8, v0
	v_add3_u32 v0, s41, v8, v0
	v_add_u32_e32 v10, 0x2400, v9
	v_add_u32_e32 v11, 0x2400, v0
	s_waitcnt vmcnt(5)
	ds_write_b128 v9, v[114:117]
	s_waitcnt vmcnt(4)
	ds_write_b128 v10, v[118:121]
	s_waitcnt vmcnt(3)
	ds_write_b128 v9, v[122:125] offset:62464
	s_waitcnt vmcnt(2)
	ds_write_b128 v10, v[126:129] offset:62464
	s_waitcnt vmcnt(1)
	ds_write_b128 v0, v[130:133] offset:144
	s_waitcnt vmcnt(0)
	ds_write_b128 v11, v[134:137] offset:144
	s_mov_b64 s[24:25], 0

; __device__ __forceinline__ unsigned pk2(float lo, float hi) { unsigned r; asm("v_cvt_pk_bf16_f32 %0, %1, %2" : "=v"(r) : "v"(lo), "v"(hi)); return r; }
; __device__ __forceinline__ float sigmoidf_(float x) { return __builtin_amdgcn_rcpf(1.f + __builtin_amdgcn_exp2f(x * -1.4426950408889634f)); }
; __device__ __forceinline__ void rwkv_out_phase(const bf16* Z, const RwkvW w, const bf16* Wl, const float* Ub, const bf16* RHO, const bf16* Y0, const float* BON, bf16* MIX, unsigned char* lds) {
;     ...
;         for (int ci = tid; ci < 2048; ci += NTHR) { const int j = ci >> 4, c8 = (ci & 15) * 8; const bf16* zc = Z + (rowbase + j) * EVEN_IN + 3712 + c8;
;             const u32x4 cg = *(const u32x4*)zc; u32x4 pg = {0u, 0u, 0u, 0u}; if (c > 0 || j > 0) pg = *(const u32x4*)(zc - EVEN_IN);
;             const f32x4 m0 = *(const f32x4*)(w.mu + 1664 + c8), m1 = *(const f32x4*)(w.mu + 1668 + c8); u32x4 og;
; #pragma unroll
;             for (int x = 0; x < 4; ++x) { const float c0 = __uint_as_float(cg[x] << 16), c1 = __uint_as_float(cg[x] & 0xffff0000u), p0 = __uint_as_float(pg[x] << 16), p1 = __uint_as_float(pg[x] & 0xffff0000u);
;                 const float ma = x < 2 ? m0[2 * x] : m1[2 * x - 4], mb = x < 2 ? m0[2 * x + 1] : m1[2 * x - 3];
;                 og[x] = pk2(sigmoidf_(c0 + ma * (p0 - c0)), sigmoidf_(c1 + mb * (p1 - c1))); }
;             *(u32x4*)(AG + j * 136 + c8) = og; }
.LBB0_655:
	s_or_b64 exec, exec, s[18:19]
	s_and_saveexec_b64 s[18:19], s[4:5]
	s_cbranch_execz .LBB0_641
	s_cmp_lg_u32 s39, 0
	s_cselect_b64 s[22:23], -1, 0
	v_ashrrev_i32_e32 v10, 4, v72
	v_ashrrev_i32_e32 v11, 31, v10
	v_lshl_add_u64 v[2:3], s[16:17], 0, v[10:11]
	v_mov_b64_e32 v[4:5], s[94:95]
	v_mad_u64_u32 v[4:5], s[24:25], v2, s65, v[4:5]
	v_mov_b32_e32 v0, v5
	v_and_b32_e32 v16, 0x78, v50
	v_mad_u64_u32 v[2:3], s[24:25], v3, s65, v[0:1]
	v_mov_b32_e32 v5, v2
	v_lshlrev_b32_e32 v0, 1, v16
	v_lshl_add_u64 v[12:13], v[4:5], 0, v[0:1]
	v_lshlrev_b32_e32 v11, 2, v16
	global_load_dwordx4 v[148:151], v11, s[14:15]
	global_load_dwordx4 v[152:155], v11, s[14:15] offset:16
	v_add_co_u32_e32 v2, vcc, 0x1000, v12
	s_mov_b64 s[20:21], 0x3c000
	s_nop 0
	v_addc_co_u32_e32 v3, vcc, 0, v13, vcc
	v_mov_b32_e32 v130, 0
	v_mov_b32_e32 v131, 0
	v_mov_b32_e32 v132, 0
	v_mov_b32_e32 v133, 0
	v_add_co_u32_e32 v24, vcc, 0xfffff000, v2
	s_nop 1
	v_addc_co_u32_e32 v25, vcc, -1, v3, vcc
	global_load_dwordx4 v[114:117], v[2:3], off offset:3328
	v_cmp_lt_i32_e32 vcc, 0, v10
	s_or_b64 s[40:41], s[22:23], vcc
	s_and_saveexec_b64 s[24:25], s[40:41]
	global_load_dwordx4 v[130:133], v[24:25], off offset:-256
	s_or_b64 exec, exec, s[24:25]
	v_lshl_add_u64 v[2:3], v[2:3], 0, s[20:21]
	v_lshl_add_u64 v[24:25], v[24:25], 0, s[20:21]
	global_load_dwordx4 v[118:121], v[2:3], off offset:3328
	global_load_dwordx4 v[134:137], v[24:25], off offset:-256
	v_lshl_add_u64 v[2:3], v[2:3], 0, s[20:21]
	v_lshl_add_u64 v[24:25], v[24:25], 0, s[20:21]
	global_load_dwordx4 v[122:125], v[2:3], off offset:3328
	global_load_dwordx4 v[138:141], v[24:25], off offset:-256
	v_lshl_add_u64 v[2:3], v[2:3], 0, s[20:21]
	v_lshl_add_u64 v[24:25], v[24:25], 0, s[20:21]
	global_load_dwordx4 v[126:129], v[2:3], off offset:3328
	global_load_dwordx4 v[142:145], v[24:25], off offset:-256
	v_mul_lo_u32 v10, v10, s88
	v_add3_u32 v0, 0, v10, v0
	s_waitcnt vmcnt(6)
	v_lshlrev_b32_e32 v11, 16, v130
	v_lshlrev_b32_e32 v12, 16, v114
	v_and_b32_e32 v114, 0xffff0000, v114
	v_and_b32_e32 v130, 0xffff0000, v130
	v_lshlrev_b32_e32 v13, 16, v131
	v_lshlrev_b32_e32 v24, 16, v115
	v_and_b32_e32 v115, 0xffff0000, v115
	v_and_b32_e32 v131, 0xffff0000, v131
	v_lshlrev_b32_e32 v15, 16, v132
	v_lshlrev_b32_e32 v26, 16, v116
	v_and_b32_e32 v116, 0xffff0000, v116
	v_and_b32_e32 v132, 0xffff0000, v132
	v_lshlrev_b32_e32 v25, 16, v133
	v_lshlrev_b32_e32 v28, 16, v117
	v_and_b32_e32 v117, 0xffff0000, v117
	v_and_b32_e32 v133, 0xffff0000, v133
	v_sub_f32_e32 v130, v130, v114
	v_sub_f32_e32 v11, v11, v12
	v_sub_f32_e32 v131, v131, v115
	v_sub_f32_e32 v13, v13, v24
	v_sub_f32_e32 v132, v132, v116
	v_sub_f32_e32 v15, v15, v26
	v_sub_f32_e32 v133, v133, v117
	v_sub_f32_e32 v25, v25, v28
	v_fmac_f32_e32 v114, v149, v130
	v_fmac_f32_e32 v12, v148, v11
	v_fmac_f32_e32 v115, v151, v131
	v_fmac_f32_e32 v24, v150, v13
	v_fmac_f32_e32 v116, v153, v132
	v_fmac_f32_e32 v26, v152, v15
	v_fmac_f32_e32 v117, v155, v133
	v_fmac_f32_e32 v28, v154, v25
	v_mul_f32_e32 v114, 0xbfb8aa3b, v114
	v_mul_f32_e32 v115, 0xbfb8aa3b, v115
	v_mul_f32_e32 v116, 0xbfb8aa3b, v116
	v_mul_f32_e32 v117, 0xbfb8aa3b, v117
	v_mul_f32_e32 v12, 0xbfb8aa3b, v12
	v_mul_f32_e32 v24, 0xbfb8aa3b, v24
	v_mul_f32_e32 v26, 0xbfb8aa3b, v26
	v_mul_f32_e32 v28, 0xbfb8aa3b, v28
	v_exp_f32_e32 v114, v114
	v_exp_f32_e32 v115, v115
	v_exp_f32_e32 v116, v116
	v_exp_f32_e32 v117, v117
	v_exp_f32_e32 v12, v12
	v_exp_f32_e32 v24, v24
	v_exp_f32_e32 v26, v26
	v_exp_f32_e32 v28, v28
	v_add_f32_e32 v114, 1.0, v114
	v_add_f32_e32 v115, 1.0, v115
	v_add_f32_e32 v116, 1.0, v116
	v_add_f32_e32 v117, 1.0, v117
	v_add_f32_e32 v12, 1.0, v12
	v_add_f32_e32 v24, 1.0, v24
	v_add_f32_e32 v26, 1.0, v26
	v_add_f32_e32 v28, 1.0, v28
	v_rcp_f32_e32 v114, v114
	v_rcp_f32_e32 v115, v115
	v_rcp_f32_e32 v116, v116
	v_rcp_f32_e32 v117, v117
	v_rcp_f32_e32 v12, v12
	v_rcp_f32_e32 v24, v24
	v_rcp_f32_e32 v26, v26
	v_rcp_f32_e32 v28, v28
	s_nop 0
	v_cvt_pk_bf16_f32 v114, v12, v114
	v_cvt_pk_bf16_f32 v115, v24, v115
	v_cvt_pk_bf16_f32 v116, v26, v116
	v_cvt_pk_bf16_f32 v117, v28, v117
	ds_write_b128 v0, v[114:117] offset:27648
	s_waitcnt vmcnt(4)
	v_lshlrev_b32_e32 v11, 16, v134
	v_lshlrev_b32_e32 v12, 16, v118
	v_and_b32_e32 v118, 0xffff0000, v118
	v_and_b32_e32 v134, 0xffff0000, v134
	v_lshlrev_b32_e32 v13, 16, v135
	v_lshlrev_b32_e32 v24, 16, v119
	v_and_b32_e32 v119, 0xffff0000, v119
	v_and_b32_e32 v135, 0xffff0000, v135
	v_lshlrev_b32_e32 v15, 16, v136
	v_lshlrev_b32_e32 v26, 16, v120
	v_and_b32_e32 v120, 0xffff0000, v120
	v_and_b32_e32 v136, 0xffff0000, v136
	v_lshlrev_b32_e32 v25, 16, v137
	v_lshlrev_b32_e32 v28, 16, v121
	v_and_b32_e32 v121, 0xffff0000, v121
	v_and_b32_e32 v137, 0xffff0000, v137
	v_sub_f32_e32 v134, v134, v118
	v_sub_f32_e32 v11, v11, v12
	v_sub_f32_e32 v135, v135, v119
	v_sub_f32_e32 v13, v13, v24
	v_sub_f32_e32 v136, v136, v120
	v_sub_f32_e32 v15, v15, v26
	v_sub_f32_e32 v137, v137, v121
	v_sub_f32_e32 v25, v25, v28
	v_fmac_f32_e32 v118, v149, v134
	v_fmac_f32_e32 v12, v148, v11
	v_fmac_f32_e32 v119, v151, v135
	v_fmac_f32_e32 v24, v150, v13
	v_fmac_f32_e32 v120, v153, v136
	v_fmac_f32_e32 v26, v152, v15
	v_fmac_f32_e32 v121, v155, v137
	v_fmac_f32_e32 v28, v154, v25
	v_mul_f32_e32 v118, 0xbfb8aa3b, v118
	v_mul_f32_e32 v119, 0xbfb8aa3b, v119
	v_mul_f32_e32 v120, 0xbfb8aa3b, v120
	v_mul_f32_e32 v121, 0xbfb8aa3b, v121
	v_mul_f32_e32 v12, 0xbfb8aa3b, v12
	v_mul_f32_e32 v24, 0xbfb8aa3b, v24
	v_mul_f32_e32 v26, 0xbfb8aa3b, v26
	v_mul_f32_e32 v28, 0xbfb8aa3b, v28
	v_exp_f32_e32 v118, v118
	v_exp_f32_e32 v119, v119
	v_exp_f32_e32 v120, v120
	v_exp_f32_e32 v121, v121
	v_exp_f32_e32 v12, v12
	v_exp_f32_e32 v24, v24
	v_exp_f32_e32 v26, v26
	v_exp_f32_e32 v28, v28
	v_add_f32_e32 v118, 1.0, v118
	v_add_f32_e32 v119, 1.0, v119
	v_add_f32_e32 v120, 1.0, v120
	v_add_f32_e32 v121, 1.0, v121
	v_add_f32_e32 v12, 1.0, v12
	v_add_f32_e32 v24, 1.0, v24
	v_add_f32_e32 v26, 1.0, v26
	v_add_f32_e32 v28, 1.0, v28
	v_rcp_f32_e32 v118, v118
	v_rcp_f32_e32 v119, v119
	v_rcp_f32_e32 v120, v120
	v_rcp_f32_e32 v121, v121
	v_rcp_f32_e32 v12, v12
	v_rcp_f32_e32 v24, v24
	v_rcp_f32_e32 v26, v26
	v_rcp_f32_e32 v28, v28
	s_nop 0
	v_cvt_pk_bf16_f32 v118, v12, v118
	v_cvt_pk_bf16_f32 v119, v24, v119
	v_cvt_pk_bf16_f32 v120, v26, v120
	v_cvt_pk_bf16_f32 v121, v28, v121
	ds_write_b128 v0, v[118:121] offset:36352
	s_waitcnt vmcnt(2)
; __device__ __forceinline__ unsigned pk2(float lo, float hi) { unsigned r; asm("v_cvt_pk_bf16_f32 %0, %1, %2" : "=v"(r) : "v"(lo), "v"(hi)); return r; }
; __device__ __forceinline__ float sigmoidf_(float x) { return __builtin_amdgcn_rcpf(1.f + __builtin_amdgcn_exp2f(x * -1.4426950408889634f)); }
; __device__ __forceinline__ void rwkv_out_phase(const bf16* Z, const RwkvW w, const bf16* Wl, const float* Ub, const bf16* RHO, const bf16* Y0, const float* BON, bf16* MIX, unsigned char* lds) {
;     ...
;         for (int ci = tid; ci < 2048; ci += NTHR) { const int j = ci >> 4, c8 = (ci & 15) * 8; const bf16* zc = Z + (rowbase + j) * EVEN_IN + 3712 + c8;
;             const u32x4 cg = *(const u32x4*)zc; u32x4 pg = {0u, 0u, 0u, 0u}; if (c > 0 || j > 0) pg = *(const u32x4*)(zc - EVEN_IN);
;             const f32x4 m0 = *(const f32x4*)(w.mu + 1664 + c8), m1 = *(const f32x4*)(w.mu + 1668 + c8); u32x4 og;
; #pragma unroll
;             for (int x = 0; x < 4; ++x) { const float c0 = __uint_as_float(cg[x] << 16), c1 = __uint_as_float(cg[x] & 0xffff0000u), p0 = __uint_as_float(pg[x] << 16), p1 = __uint_as_float(pg[x] & 0xffff0000u);
;                 const float ma = x < 2 ? m0[2 * x] : m1[2 * x - 4], mb = x < 2 ? m0[2 * x + 1] : m1[2 * x - 3];
;                 og[x] = pk2(sigmoidf_(c0 + ma * (p0 - c0)), sigmoidf_(c1 + mb * (p1 - c1))); }
;             *(u32x4*)(AG + j * 136 + c8) = og; }
	v_lshlrev_b32_e32 v11, 16, v138
	v_lshlrev_b32_e32 v12, 16, v122
	v_and_b32_e32 v122, 0xffff0000, v122
	v_and_b32_e32 v138, 0xffff0000, v138
	v_lshlrev_b32_e32 v13, 16, v139
	v_lshlrev_b32_e32 v24, 16, v123
	v_and_b32_e32 v123, 0xffff0000, v123
	v_and_b32_e32 v139, 0xffff0000, v139
	v_lshlrev_b32_e32 v15, 16, v140
	v_lshlrev_b32_e32 v26, 16, v124
	v_and_b32_e32 v124, 0xffff0000, v124
	v_and_b32_e32 v140, 0xffff0000, v140
	v_lshlrev_b32_e32 v25, 16, v141
	v_lshlrev_b32_e32 v28, 16, v125
	v_and_b32_e32 v125, 0xffff0000, v125
	v_and_b32_e32 v141, 0xffff0000, v141
	v_sub_f32_e32 v138, v138, v122
	v_sub_f32_e32 v11, v11, v12
	v_sub_f32_e32 v139, v139, v123
	v_sub_f32_e32 v13, v13, v24
	v_sub_f32_e32 v140, v140, v124
	v_sub_f32_e32 v15, v15, v26
	v_sub_f32_e32 v141, v141, v125
	v_sub_f32_e32 v25, v25, v28
	v_fmac_f32_e32 v122, v149, v138
	v_fmac_f32_e32 v12, v148, v11
	v_fmac_f32_e32 v123, v151, v139
	v_fmac_f32_e32 v24, v150, v13
	v_fmac_f32_e32 v124, v153, v140
	v_fmac_f32_e32 v26, v152, v15
	v_fmac_f32_e32 v125, v155, v141
	v_fmac_f32_e32 v28, v154, v25
	v_mul_f32_e32 v122, 0xbfb8aa3b, v122
	v_mul_f32_e32 v123, 0xbfb8aa3b, v123
	v_mul_f32_e32 v124, 0xbfb8aa3b, v124
	v_mul_f32_e32 v125, 0xbfb8aa3b, v125
	v_mul_f32_e32 v12, 0xbfb8aa3b, v12
	v_mul_f32_e32 v24, 0xbfb8aa3b, v24
	v_mul_f32_e32 v26, 0xbfb8aa3b, v26
	v_mul_f32_e32 v28, 0xbfb8aa3b, v28
	v_exp_f32_e32 v122, v122
	v_exp_f32_e32 v123, v123
	v_exp_f32_e32 v124, v124
	v_exp_f32_e32 v125, v125
	v_exp_f32_e32 v12, v12
	v_exp_f32_e32 v24, v24
	v_exp_f32_e32 v26, v26
	v_exp_f32_e32 v28, v28
	v_add_f32_e32 v122, 1.0, v122
	v_add_f32_e32 v123, 1.0, v123
	v_add_f32_e32 v124, 1.0, v124
	v_add_f32_e32 v125, 1.0, v125
	v_add_f32_e32 v12, 1.0, v12
	v_add_f32_e32 v24, 1.0, v24
	v_add_f32_e32 v26, 1.0, v26
	v_add_f32_e32 v28, 1.0, v28
	v_rcp_f32_e32 v122, v122
	v_rcp_f32_e32 v123, v123
	v_rcp_f32_e32 v124, v124
	v_rcp_f32_e32 v125, v125
	v_rcp_f32_e32 v12, v12
	v_rcp_f32_e32 v24, v24
	v_rcp_f32_e32 v26, v26
	v_rcp_f32_e32 v28, v28
	s_nop 0
	v_cvt_pk_bf16_f32 v122, v12, v122
	v_cvt_pk_bf16_f32 v123, v24, v123
	v_cvt_pk_bf16_f32 v124, v26, v124
	v_cvt_pk_bf16_f32 v125, v28, v125
	ds_write_b128 v0, v[122:125] offset:45056
	s_waitcnt vmcnt(0)
	v_lshlrev_b32_e32 v11, 16, v142
	v_lshlrev_b32_e32 v12, 16, v126
	v_and_b32_e32 v126, 0xffff0000, v126
	v_and_b32_e32 v142, 0xffff0000, v142
	v_lshlrev_b32_e32 v13, 16, v143
	v_lshlrev_b32_e32 v24, 16, v127
	v_and_b32_e32 v127, 0xffff0000, v127
	v_and_b32_e32 v143, 0xffff0000, v143
	v_lshlrev_b32_e32 v15, 16, v144
	v_lshlrev_b32_e32 v26, 16, v128
	v_and_b32_e32 v128, 0xffff0000, v128
	v_and_b32_e32 v144, 0xffff0000, v144
	v_lshlrev_b32_e32 v25, 16, v145
	v_lshlrev_b32_e32 v28, 16, v129
	v_and_b32_e32 v129, 0xffff0000, v129
	v_and_b32_e32 v145, 0xffff0000, v145
	v_sub_f32_e32 v142, v142, v126
	v_sub_f32_e32 v11, v11, v12
	v_sub_f32_e32 v143, v143, v127
	v_sub_f32_e32 v13, v13, v24
	v_sub_f32_e32 v144, v144, v128
	v_sub_f32_e32 v15, v15, v26
	v_sub_f32_e32 v145, v145, v129
	v_sub_f32_e32 v25, v25, v28
	v_fmac_f32_e32 v126, v149, v142
	v_fmac_f32_e32 v12, v148, v11
	v_fmac_f32_e32 v127, v151, v143
	v_fmac_f32_e32 v24, v150, v13
	v_fmac_f32_e32 v128, v153, v144
	v_fmac_f32_e32 v26, v152, v15
	v_fmac_f32_e32 v129, v155, v145
	v_fmac_f32_e32 v28, v154, v25
	v_mul_f32_e32 v126, 0xbfb8aa3b, v126
	v_mul_f32_e32 v127, 0xbfb8aa3b, v127
	v_mul_f32_e32 v128, 0xbfb8aa3b, v128
	v_mul_f32_e32 v129, 0xbfb8aa3b, v129
	v_mul_f32_e32 v12, 0xbfb8aa3b, v12
	v_mul_f32_e32 v24, 0xbfb8aa3b, v24
	v_mul_f32_e32 v26, 0xbfb8aa3b, v26
	v_mul_f32_e32 v28, 0xbfb8aa3b, v28
	v_exp_f32_e32 v126, v126
	v_exp_f32_e32 v127, v127
	v_exp_f32_e32 v128, v128
	v_exp_f32_e32 v129, v129
	v_exp_f32_e32 v12, v12
	v_exp_f32_e32 v24, v24
	v_exp_f32_e32 v26, v26
	v_exp_f32_e32 v28, v28
	v_add_f32_e32 v126, 1.0, v126
	v_add_f32_e32 v127, 1.0, v127
	v_add_f32_e32 v128, 1.0, v128
	v_add_f32_e32 v129, 1.0, v129
	v_add_f32_e32 v12, 1.0, v12
	v_add_f32_e32 v24, 1.0, v24
	v_add_f32_e32 v26, 1.0, v26
	v_add_f32_e32 v28, 1.0, v28
	v_rcp_f32_e32 v126, v126
	v_rcp_f32_e32 v127, v127
	v_rcp_f32_e32 v128, v128
	v_rcp_f32_e32 v129, v129
	v_rcp_f32_e32 v12, v12
	v_rcp_f32_e32 v24, v24
	v_rcp_f32_e32 v26, v26
	v_rcp_f32_e32 v28, v28
	s_nop 0
	v_cvt_pk_bf16_f32 v126, v12, v126
	v_cvt_pk_bf16_f32 v127, v24, v127
	v_cvt_pk_bf16_f32 v128, v26, v128
	v_cvt_pk_bf16_f32 v129, v28, v129
	ds_write_b128 v0, v[126:129] offset:53760
	s_branch .LBB0_641
